# in-proj unit decode: row-group size is always 8 for this shape, generic division replaced by shift and mask
# baseline (speedup 1.0000x reference)
.LBB0_155:
	s_ashr_i32 s12, s14, 3
	s_add_i32 s12, s16, s12
	s_ashr_i32 s13, s12, 31
	s_lshr_b32 s13, s13, 24
	s_add_i32 s13, s12, s13
	s_ashr_i32 s14, s13, 8
	s_lshl_b32 s14, s14, 3
	s_and_b32 s13, s13, 0xffffff00
	s_sub_i32 s13, s12, s13
	s_lshr_b32 s12, s13, 3
	s_and_b32 s13, s13, 7
	s_add_i32 s14, s14, s13
	s_mov_b64 s[16:17], -1
